# first arriver of each XCD starts an L2 write-back early at chip-wide barriers 1-3 (last arriver's write-back unchanged) on top of v058
# speedup vs baseline: 1.0022x; 1.0022x over previous
.LBB0_76:
	s_or_b64 exec, exec, s[10:11]
	v_cvt_f32_u32_e32 v4, v2
	s_waitcnt vmcnt(0)
	v_readfirstlane_b32 s6, v3
	v_sub_u32_e32 v3, 0, v2
	v_rcp_iflag_f32_e32 v4, v4
	v_add_u32_e32 v5, s6, v1
	v_mul_f32_e32 v4, 0x4f7ffffe, v4
	v_cvt_u32_f32_e32 v4, v4
	v_mul_lo_u32 v1, v3, v4
	v_mul_hi_u32 v1, v4, v1
	v_add_u32_e32 v1, v4, v1
	v_mul_hi_u32 v1, v5, v1
	v_mul_lo_u32 v3, v1, v2
	v_sub_u32_e32 v3, v5, v3
	v_add_u32_e32 v4, 1, v1
	v_cmp_ge_u32_e32 vcc, v3, v2
	s_nop 1
	v_cndmask_b32_e32 v1, v1, v4, vcc
	v_sub_u32_e32 v4, v3, v2
	v_cndmask_b32_e32 v3, v3, v4, vcc
	v_add_u32_e32 v4, 1, v1
	v_cmp_ge_u32_e32 vcc, v3, v2
	v_add_u32_e32 v3, 1, v5
	s_nop 0
	v_cndmask_b32_e32 v1, v1, v4, vcc
	v_mul_lo_u32 v4, v2, v1
	v_add_u32_e32 v2, v4, v2
	v_cmp_ne_u32_e32 vcc, v3, v2
	s_and_saveexec_b64 s[6:7], vcc
	s_xor_b64 s[6:7], exec, s[6:7]
	s_cbranch_execz .LBB0_90
	v_cmp_eq_u32_e32 vcc, v5, v4
	s_cbranch_vccz .Lfwb_b1
	buffer_wbl2 sc1
.Lfwb_b1:
	s_waitcnt lgkmcnt(0)
	v_mov_b32_e32 v0, 0x2000
	global_load_dword v0, v0, s[4:5] offset:1024 sc1
	s_add_u32 s34, s4, 0x2400
	s_addc_u32 s35, s5, 0
	s_waitcnt vmcnt(0)
	v_cmp_eq_u32_e32 vcc, v0, v1
	s_and_saveexec_b64 s[10:11], vcc
	s_cbranch_execz .LBB0_89
	s_add_u32 s18, s66, 0x40200
	s_addc_u32 s19, s67, 0
	s_mov_b32 s20, 1
	s_mov_b64 s[46:47], 0
	v_mov_b32_e32 v0, 0
	s_branch .LBB0_80

.LBB0_235:
	s_or_b64 exec, exec, s[52:53]
	v_cvt_f32_u32_e32 v4, v2
	s_waitcnt vmcnt(0)
	v_readfirstlane_b32 s21, v3
	v_sub_u32_e32 v3, 0, v2
	v_rcp_iflag_f32_e32 v4, v4
	v_add_u32_e32 v5, s21, v1
	v_mul_f32_e32 v4, 0x4f7ffffe, v4
	v_cvt_u32_f32_e32 v4, v4
	v_mul_lo_u32 v1, v3, v4
	v_mul_hi_u32 v1, v4, v1
	v_add_u32_e32 v1, v4, v1
	v_mul_hi_u32 v1, v5, v1
	v_mul_lo_u32 v3, v1, v2
	v_sub_u32_e32 v3, v5, v3
	v_add_u32_e32 v4, 1, v1
	v_cmp_ge_u32_e32 vcc, v3, v2
	s_nop 1
	v_cndmask_b32_e32 v1, v1, v4, vcc
	v_sub_u32_e32 v4, v3, v2
	v_cndmask_b32_e32 v3, v3, v4, vcc
	v_add_u32_e32 v4, 1, v1
	v_cmp_ge_u32_e32 vcc, v3, v2
	v_add_u32_e32 v3, 1, v5
	s_nop 0
	v_cndmask_b32_e32 v1, v1, v4, vcc
	v_mul_lo_u32 v4, v2, v1
	v_add_u32_e32 v2, v4, v2
	v_cmp_ne_u32_e32 vcc, v3, v2
	s_and_saveexec_b64 s[48:49], vcc
	s_xor_b64 s[48:49], exec, s[48:49]
	s_cbranch_execz .LBB0_249
	v_cmp_eq_u32_e32 vcc, v5, v4
	s_cbranch_vccz .Lfwb_b2
	buffer_wbl2 sc1
.Lfwb_b2:
	s_waitcnt lgkmcnt(0)
	v_mov_b32_e32 v0, 0x2000
	global_load_dword v0, v0, s[4:5] offset:1024 sc1
	s_add_u32 s56, s4, 0x2400
	s_addc_u32 s57, s5, 0
	s_waitcnt vmcnt(0)
	v_cmp_eq_u32_e32 vcc, v0, v1
	s_and_saveexec_b64 s[52:53], vcc
	s_cbranch_execz .LBB0_248
	s_add_u32 s54, s66, 0x40200
	s_addc_u32 s55, s67, 0
	s_mov_b32 s21, 1
	s_mov_b64 s[58:59], 0
	v_mov_b32_e32 v0, 0
	s_branch .LBB0_239

.LBB0_358:
	s_or_b64 exec, exec, s[10:11]
	v_cvt_f32_u32_e32 v4, v2
	s_waitcnt vmcnt(0)
	v_readfirstlane_b32 s8, v3
	v_sub_u32_e32 v3, 0, v2
	v_rcp_iflag_f32_e32 v4, v4
	v_add_u32_e32 v5, s8, v1
	v_mul_f32_e32 v4, 0x4f7ffffe, v4
	v_cvt_u32_f32_e32 v4, v4
	v_mul_lo_u32 v1, v3, v4
	v_mul_hi_u32 v1, v4, v1
	v_add_u32_e32 v1, v4, v1
	v_mul_hi_u32 v1, v5, v1
	v_mul_lo_u32 v3, v1, v2
	v_sub_u32_e32 v3, v5, v3
	v_add_u32_e32 v4, 1, v1
	v_cmp_ge_u32_e32 vcc, v3, v2
	s_nop 1
	v_cndmask_b32_e32 v1, v1, v4, vcc
	v_sub_u32_e32 v4, v3, v2
	v_cndmask_b32_e32 v3, v3, v4, vcc
	v_add_u32_e32 v4, 1, v1
	v_cmp_ge_u32_e32 vcc, v3, v2
	v_add_u32_e32 v3, 1, v5
	s_nop 0
	v_cndmask_b32_e32 v1, v1, v4, vcc
	v_mul_lo_u32 v4, v2, v1
	v_add_u32_e32 v2, v4, v2
	v_cmp_ne_u32_e32 vcc, v3, v2
	s_and_saveexec_b64 s[8:9], vcc
	s_xor_b64 s[8:9], exec, s[8:9]
	s_cbranch_execz .LBB0_372
	v_cmp_eq_u32_e32 vcc, v5, v4
	s_cbranch_vccz .Lfwb_b3
	buffer_wbl2 sc1
.Lfwb_b3:
	s_waitcnt lgkmcnt(0)
	v_mov_b32_e32 v0, 0x2000
	global_load_dword v0, v0, s[4:5] offset:1024 sc1
	s_add_u32 s14, s4, 0x2400
	s_addc_u32 s15, s5, 0
	s_waitcnt vmcnt(0)
	v_cmp_eq_u32_e32 vcc, v0, v1
	s_and_saveexec_b64 s[10:11], vcc
	s_cbranch_execz .LBB0_371
	s_add_u32 s12, s66, 0x40200
	s_addc_u32 s13, s67, 0
	s_mov_b32 s20, 1
	s_mov_b64 s[16:17], 0
	v_mov_b32_e32 v0, 0
	s_branch .LBB0_362
